# SwiGLU epilogues: hoist the 8 row-ss loads to the epilogue head, single wait
# speedup vs baseline: 1.0078x; 1.0078x over previous
; __device__ __forceinline__ float sigmoidf_(float x) { return __builtin_amdgcn_rcpf(1.f + __expf(-x)); }
;     __device__ __forceinline__ void operator()(const AccT& acc, const Unit& u, int wr, int wc, int fr, int fq) const {
;         const int row0 = u.pm * BM + wr * 64 + fr, col = u.pn * 128 + wc * 32 + 8 * fq;
; #pragma unroll
;         for (int ai = 0; ai < 2; ++ai)
; #pragma unroll
;             for (int m = 0; m < 4; ++m) {
;                 const int row = row0 + ai * HALF + m * 16;
;                 const float rs = rsqrtf(ss[row] * (1.f / 1024.f) + EPS);
;                 float o[8];
; #pragma unroll
;                 for (int n = 0; n < 2; ++n)
; #pragma unroll
;                     for (int j = 0; j < 4; ++j) { const float gt = acc[ai][0][m][n][j] * rs, up = acc[ai][1][m][n][j] * rs; o[n * 4 + j] = gt * up * sigmoidf_(gt); }
;                 *(u32x4*)(O + (size_t)row * FF + col) = pack8(o);
;             }
;     }
.LBB0_226:
	v_lshl_add_u32 v146, s4, 8, v129
	v_ashrrev_i32_e32 v147, 31, v146
	v_lshl_add_u64 v[148:149], v[146:147], 2, s[70:71]
	global_load_dword v147, v[148:149], off
	global_load_dword v233, v[148:149], off offset:64
	global_load_dword v234, v[148:149], off offset:128
	global_load_dword v235, v[148:149], off offset:192
	global_load_dword v236, v[148:149], off offset:512
	global_load_dword v237, v[148:149], off offset:576
	global_load_dword v238, v[148:149], off offset:640
	global_load_dword v239, v[148:149], off offset:704
	v_mov_b32_e32 v166, v122
	v_mov_b32_e32 v167, v114
	v_mov_b32_e32 v114, v123
	v_lshl_or_b32 v158, s5, 7, v151
	v_mov_b32_e32 v160, v124
	v_mov_b32_e32 v161, v116
	v_mov_b32_e32 v116, v125
	v_mov_b32_e32 v124, v126
	v_mov_b32_e32 v125, v118
	v_mov_b32_e32 v118, v127
	v_mov_b32_e32 v126, v120
	v_mov_b32_e32 v127, v112
	v_mov_b32_e32 v112, v121
	v_mov_b64_e32 v[120:121], s[44:45]
	v_ashrrev_i32_e32 v159, 31, v158
	v_mad_i64_i32 v[168:169], s[4:5], v146, s79, v[120:121]
	s_waitcnt vmcnt(0)
	v_fmamk_f32 v122, v147, 0x3a800000, v155
	v_mul_f32_e32 v123, 0x4b800000, v122
	v_cmp_gt_f32_e32 vcc, s78, v122
	s_nop 1
	v_cndmask_b32_e32 v122, v122, v123, vcc
	v_rsq_f32_e32 v147, v122
	v_lshlrev_b64 v[122:123], 1, v[158:159]
	v_lshl_add_u64 v[158:159], v[168:169], 0, v[122:123]
	v_mul_f32_e32 v165, 0x45800000, v147
	v_cndmask_b32_e32 v168, v147, v165, vcc
	v_pk_mul_f32 v[114:115], v[114:115], v[168:169] op_sel_hi:[1,0]
	v_pk_mul_f32 v[160:161], v[160:161], v[168:169] op_sel_hi:[1,0]
	v_pk_mul_f32 v[116:117], v[116:117], v[168:169] op_sel_hi:[1,0]
	v_pk_mul_f32 v[124:125], v[124:125], v[168:169] op_sel_hi:[1,0]
	v_pk_mul_f32 v[118:119], v[118:119], v[168:169] op_sel_hi:[1,0]
	v_pk_mul_f32 v[126:127], v[126:127], v[168:169] op_sel_hi:[1,0]
	v_pk_mul_f32 v[112:113], v[112:113], v[168:169] op_sel_hi:[1,0]
	v_pk_mul_f32 v[166:167], v[166:167], v[168:169] op_sel_hi:[1,0]
	v_mul_f32_e32 v115, v114, v115
	v_mul_f32_e32 v114, 0xbfb8aa3b, v114
	v_mul_f32_e32 v147, v160, v161
	v_mul_f32_e32 v160, 0xbfb8aa3b, v160
	v_mul_f32_e32 v117, v116, v117
	v_mul_f32_e32 v116, 0xbfb8aa3b, v116
	v_mul_f32_e32 v125, v124, v125
	v_mul_f32_e32 v124, 0xbfb8aa3b, v124
	v_mul_f32_e32 v119, v118, v119
	v_mul_f32_e32 v118, 0xbfb8aa3b, v118
	v_mul_f32_e32 v127, v126, v127
	v_mul_f32_e32 v126, 0xbfb8aa3b, v126
	v_mul_f32_e32 v113, v112, v113
	v_mul_f32_e32 v112, 0xbfb8aa3b, v112
	v_mul_f32_e32 v165, 0xbfb8aa3b, v166
	v_exp_f32_e32 v114, v114
	v_exp_f32_e32 v160, v160
	v_exp_f32_e32 v116, v116
	v_exp_f32_e32 v124, v124
	v_exp_f32_e32 v118, v118
	v_exp_f32_e32 v126, v126
	v_exp_f32_e32 v112, v112
	v_exp_f32_e32 v165, v165
	v_add_f32_e32 v114, 1.0, v114
	v_add_f32_e32 v160, 1.0, v160
	v_add_f32_e32 v116, 1.0, v116
	v_add_f32_e32 v124, 1.0, v124
	v_add_f32_e32 v118, 1.0, v118
	v_add_f32_e32 v126, 1.0, v126
	v_add_f32_e32 v112, 1.0, v112
	v_add_f32_e32 v165, 1.0, v165
	v_rcp_f32_e32 v114, v114
	v_rcp_f32_e32 v160, v160
	v_rcp_f32_e32 v116, v116
	v_rcp_f32_e32 v124, v124
	v_rcp_f32_e32 v118, v118
	v_rcp_f32_e32 v126, v126
	v_rcp_f32_e32 v112, v112
	v_rcp_f32_e32 v165, v165
	v_mul_f32_e32 v161, v166, v167
	v_mul_f32_e32 v115, v115, v114
	v_mul_f32_e32 v147, v147, v160
	v_mul_f32_e32 v116, v117, v116
	v_mul_f32_e32 v117, v125, v124
	v_mul_f32_e32 v118, v119, v118
	v_mul_f32_e32 v119, v127, v126
	v_mul_f32_e32 v124, v113, v112
	v_mul_f32_e32 v125, v161, v165
	v_cvt_pk_bf16_f32 v112, v147, v116
	v_cvt_pk_bf16_f32 v113, v117, v118
	v_cvt_pk_bf16_f32 v114, v119, v124
	v_cvt_pk_bf16_f32 v115, v125, v115
	global_store_dwordx4 v[158:159], v[112:115], off
	s_nop 0
	s_nop 0
	v_mov_b32_e32 v113, v100
	v_mov_b32_e32 v100, v109
	v_mov_b32_e32 v109, v102
	v_mov_b32_e32 v102, v111
	v_mov_b32_e32 v111, v96
	v_mov_b32_e32 v96, v105
	v_mov_b32_e32 v105, v98
	v_mov_b32_e32 v98, v107
	v_mov_b32_e32 v112, v108
	v_mov_b32_e32 v108, v110
	v_mov_b32_e32 v110, v104
	v_mov_b32_e32 v104, v106
	v_or_b32_e32 v106, 16, v146
	s_nop 0
	v_fmamk_f32 v107, v233, 0x3a800000, v155
	v_mul_f32_e32 v114, 0x4b800000, v107
	v_cmp_gt_f32_e32 vcc, s78, v107
	s_nop 1
	v_cndmask_b32_e32 v107, v107, v114, vcc
	v_rsq_f32_e32 v114, v107
	v_mad_i64_i32 v[106:107], s[4:5], v106, s79, v[120:121]
	v_lshl_add_u64 v[106:107], v[106:107], 0, v[122:123]
	v_mul_f32_e32 v115, 0x45800000, v114
	v_cndmask_b32_e32 v114, v114, v115, vcc
	v_pk_mul_f32 v[98:99], v[98:99], v[114:115] op_sel_hi:[1,0]
	v_pk_mul_f32 v[112:113], v[112:113], v[114:115] op_sel_hi:[1,0]
	v_pk_mul_f32 v[100:101], v[100:101], v[114:115] op_sel_hi:[1,0]
	v_pk_mul_f32 v[108:109], v[108:109], v[114:115] op_sel_hi:[1,0]
	v_pk_mul_f32 v[102:103], v[102:103], v[114:115] op_sel_hi:[1,0]
	v_pk_mul_f32 v[110:111], v[110:111], v[114:115] op_sel_hi:[1,0]
	v_pk_mul_f32 v[96:97], v[96:97], v[114:115] op_sel_hi:[1,0]
	v_pk_mul_f32 v[104:105], v[104:105], v[114:115] op_sel_hi:[1,0]
	v_mul_f32_e32 v99, v98, v99
	v_mul_f32_e32 v98, 0xbfb8aa3b, v98
	v_mul_f32_e32 v113, v112, v113
	v_mul_f32_e32 v112, 0xbfb8aa3b, v112
	v_mul_f32_e32 v101, v100, v101
	v_mul_f32_e32 v100, 0xbfb8aa3b, v100
	v_mul_f32_e32 v109, v108, v109
	v_mul_f32_e32 v108, 0xbfb8aa3b, v108
	v_mul_f32_e32 v103, v102, v103
	v_mul_f32_e32 v102, 0xbfb8aa3b, v102
	v_mul_f32_e32 v111, v110, v111
	v_mul_f32_e32 v110, 0xbfb8aa3b, v110
	v_mul_f32_e32 v97, v96, v97
	v_mul_f32_e32 v96, 0xbfb8aa3b, v96
	v_mul_f32_e32 v105, v104, v105
	v_mul_f32_e32 v104, 0xbfb8aa3b, v104
	v_exp_f32_e32 v98, v98
	v_exp_f32_e32 v112, v112
	v_exp_f32_e32 v100, v100
	v_exp_f32_e32 v108, v108
	v_exp_f32_e32 v102, v102
	v_exp_f32_e32 v110, v110
	v_exp_f32_e32 v96, v96
	v_exp_f32_e32 v104, v104
	v_add_f32_e32 v98, 1.0, v98
	v_add_f32_e32 v112, 1.0, v112
; __device__ __forceinline__ float sigmoidf_(float x) { return __builtin_amdgcn_rcpf(1.f + __expf(-x)); }
;     __device__ __forceinline__ void operator()(const AccT& acc, const Unit& u, int wr, int wc, int fr, int fq) const {
;         const int row0 = u.pm * BM + wr * 64 + fr, col = u.pn * 128 + wc * 32 + 8 * fq;
; #pragma unroll
;         for (int ai = 0; ai < 2; ++ai)
; #pragma unroll
;             for (int m = 0; m < 4; ++m) {
;                 const int row = row0 + ai * HALF + m * 16;
;                 const float rs = rsqrtf(ss[row] * (1.f / 1024.f) + EPS);
;                 float o[8];
; #pragma unroll
;                 for (int n = 0; n < 2; ++n)
; #pragma unroll
;                     for (int j = 0; j < 4; ++j) { const float gt = acc[ai][0][m][n][j] * rs, up = acc[ai][1][m][n][j] * rs; o[n * 4 + j] = gt * up * sigmoidf_(gt); }
;                 *(u32x4*)(O + (size_t)row * FF + col) = pack8(o);
;             }
;     }
	v_add_f32_e32 v100, 1.0, v100
	v_add_f32_e32 v108, 1.0, v108
	v_add_f32_e32 v102, 1.0, v102
	v_add_f32_e32 v110, 1.0, v110
	v_add_f32_e32 v96, 1.0, v96
	v_add_f32_e32 v104, 1.0, v104
	v_rcp_f32_e32 v98, v98
	v_rcp_f32_e32 v112, v112
	v_rcp_f32_e32 v100, v100
	v_rcp_f32_e32 v108, v108
	v_rcp_f32_e32 v102, v102
	v_rcp_f32_e32 v110, v110
	v_rcp_f32_e32 v96, v96
	v_rcp_f32_e32 v104, v104
	v_mul_f32_e32 v99, v99, v98
	v_mul_f32_e32 v112, v113, v112
	v_mul_f32_e32 v100, v101, v100
	v_mul_f32_e32 v101, v109, v108
	v_mul_f32_e32 v102, v103, v102
	v_mul_f32_e32 v103, v111, v110
	v_mul_f32_e32 v108, v97, v96
	v_mul_f32_e32 v104, v105, v104
	v_cvt_pk_bf16_f32 v96, v112, v100
	v_cvt_pk_bf16_f32 v97, v101, v102
	v_cvt_pk_bf16_f32 v98, v103, v108
	v_cvt_pk_bf16_f32 v99, v104, v99
	global_store_dwordx4 v[106:107], v[96:99], off
	s_nop 0
	s_nop 0
	v_mov_b32_e32 v97, v84
	v_mov_b32_e32 v84, v93
	v_mov_b32_e32 v93, v86
	v_mov_b32_e32 v86, v95
	v_mov_b32_e32 v95, v80
	v_mov_b32_e32 v80, v89
	v_mov_b32_e32 v89, v82
	v_mov_b32_e32 v82, v91
	v_mov_b32_e32 v96, v92
	v_mov_b32_e32 v92, v94
	v_mov_b32_e32 v94, v88
	v_mov_b32_e32 v88, v90
	v_or_b32_e32 v90, 32, v146
	s_nop 0
	v_fmamk_f32 v91, v234, 0x3a800000, v155
	v_mul_f32_e32 v98, 0x4b800000, v91
	v_cmp_gt_f32_e32 vcc, s78, v91
	s_nop 1
	v_cndmask_b32_e32 v91, v91, v98, vcc
	v_rsq_f32_e32 v98, v91
	v_mad_i64_i32 v[90:91], s[4:5], v90, s79, v[120:121]
	v_lshl_add_u64 v[90:91], v[90:91], 0, v[122:123]
	v_mul_f32_e32 v99, 0x45800000, v98
	v_cndmask_b32_e32 v98, v98, v99, vcc
	v_pk_mul_f32 v[82:83], v[82:83], v[98:99] op_sel_hi:[1,0]
	v_pk_mul_f32 v[96:97], v[96:97], v[98:99] op_sel_hi:[1,0]
	v_pk_mul_f32 v[84:85], v[84:85], v[98:99] op_sel_hi:[1,0]
	v_pk_mul_f32 v[92:93], v[92:93], v[98:99] op_sel_hi:[1,0]
	v_pk_mul_f32 v[86:87], v[86:87], v[98:99] op_sel_hi:[1,0]
	v_pk_mul_f32 v[94:95], v[94:95], v[98:99] op_sel_hi:[1,0]
	v_pk_mul_f32 v[80:81], v[80:81], v[98:99] op_sel_hi:[1,0]
	v_pk_mul_f32 v[88:89], v[88:89], v[98:99] op_sel_hi:[1,0]
	v_mul_f32_e32 v83, v82, v83
	v_mul_f32_e32 v82, 0xbfb8aa3b, v82
	v_mul_f32_e32 v97, v96, v97
	v_mul_f32_e32 v96, 0xbfb8aa3b, v96
	v_mul_f32_e32 v85, v84, v85
	v_mul_f32_e32 v84, 0xbfb8aa3b, v84
	v_mul_f32_e32 v93, v92, v93
	v_mul_f32_e32 v92, 0xbfb8aa3b, v92
	v_mul_f32_e32 v87, v86, v87
	v_mul_f32_e32 v86, 0xbfb8aa3b, v86
	v_mul_f32_e32 v95, v94, v95
	v_mul_f32_e32 v94, 0xbfb8aa3b, v94
	v_mul_f32_e32 v81, v80, v81
	v_mul_f32_e32 v80, 0xbfb8aa3b, v80
	v_mul_f32_e32 v89, v88, v89
	v_mul_f32_e32 v88, 0xbfb8aa3b, v88
	v_exp_f32_e32 v82, v82
	v_exp_f32_e32 v96, v96
	v_exp_f32_e32 v84, v84
	v_exp_f32_e32 v92, v92
	v_exp_f32_e32 v86, v86
	v_exp_f32_e32 v94, v94
	v_exp_f32_e32 v80, v80
	v_exp_f32_e32 v88, v88
	v_add_f32_e32 v82, 1.0, v82
	v_add_f32_e32 v96, 1.0, v96
	v_add_f32_e32 v84, 1.0, v84
	v_add_f32_e32 v92, 1.0, v92
	v_add_f32_e32 v86, 1.0, v86
	v_add_f32_e32 v94, 1.0, v94
	v_add_f32_e32 v80, 1.0, v80
	v_add_f32_e32 v88, 1.0, v88
	v_rcp_f32_e32 v82, v82
	v_rcp_f32_e32 v96, v96
	v_rcp_f32_e32 v84, v84
	v_rcp_f32_e32 v92, v92
	v_rcp_f32_e32 v86, v86
	v_rcp_f32_e32 v94, v94
	v_rcp_f32_e32 v80, v80
	v_rcp_f32_e32 v88, v88
	v_mul_f32_e32 v83, v83, v82
	v_mul_f32_e32 v96, v97, v96
	v_mul_f32_e32 v84, v85, v84
	v_mul_f32_e32 v85, v93, v92
	v_mul_f32_e32 v86, v87, v86
	v_mul_f32_e32 v87, v95, v94
	v_mul_f32_e32 v92, v81, v80
	v_mul_f32_e32 v88, v89, v88
	v_cvt_pk_bf16_f32 v80, v96, v84
	v_cvt_pk_bf16_f32 v81, v85, v86
	v_cvt_pk_bf16_f32 v82, v87, v92
	v_cvt_pk_bf16_f32 v83, v88, v83
	global_store_dwordx4 v[90:91], v[80:83], off
	s_nop 0
	s_nop 0
	v_mov_b32_e32 v81, v68
	v_mov_b32_e32 v68, v77
	v_mov_b32_e32 v77, v70
	v_mov_b32_e32 v70, v79
	v_mov_b32_e32 v79, v64
	v_mov_b32_e32 v64, v73
	v_mov_b32_e32 v73, v66
	v_mov_b32_e32 v66, v75
	v_mov_b32_e32 v80, v76
	v_mov_b32_e32 v76, v78
	v_mov_b32_e32 v78, v72
	v_mov_b32_e32 v72, v74
	v_or_b32_e32 v74, 48, v146
	s_nop 0
	v_fmamk_f32 v75, v235, 0x3a800000, v155
	v_mul_f32_e32 v82, 0x4b800000, v75
	v_cmp_gt_f32_e32 vcc, s78, v75
	s_nop 1
	v_cndmask_b32_e32 v75, v75, v82, vcc
	v_rsq_f32_e32 v82, v75
	v_mad_i64_i32 v[74:75], s[4:5], v74, s79, v[120:121]
	v_lshl_add_u64 v[74:75], v[74:75], 0, v[122:123]
	v_mul_f32_e32 v83, 0x45800000, v82
	v_cndmask_b32_e32 v82, v82, v83, vcc
	v_pk_mul_f32 v[66:67], v[66:67], v[82:83] op_sel_hi:[1,0]
	v_pk_mul_f32 v[80:81], v[80:81], v[82:83] op_sel_hi:[1,0]
	v_pk_mul_f32 v[68:69], v[68:69], v[82:83] op_sel_hi:[1,0]
	v_pk_mul_f32 v[76:77], v[76:77], v[82:83] op_sel_hi:[1,0]
	v_pk_mul_f32 v[70:71], v[70:71], v[82:83] op_sel_hi:[1,0]
	v_pk_mul_f32 v[78:79], v[78:79], v[82:83] op_sel_hi:[1,0]
	v_pk_mul_f32 v[64:65], v[64:65], v[82:83] op_sel_hi:[1,0]
	v_pk_mul_f32 v[72:73], v[72:73], v[82:83] op_sel_hi:[1,0]
	v_mul_f32_e32 v67, v66, v67
	v_mul_f32_e32 v66, 0xbfb8aa3b, v66
	v_mul_f32_e32 v81, v80, v81
	v_mul_f32_e32 v80, 0xbfb8aa3b, v80
	v_mul_f32_e32 v69, v68, v69
	v_mul_f32_e32 v68, 0xbfb8aa3b, v68
	v_mul_f32_e32 v77, v76, v77
	v_mul_f32_e32 v76, 0xbfb8aa3b, v76
	v_mul_f32_e32 v71, v70, v71
	v_mul_f32_e32 v70, 0xbfb8aa3b, v70
	v_mul_f32_e32 v79, v78, v79
	v_mul_f32_e32 v78, 0xbfb8aa3b, v78
	v_mul_f32_e32 v65, v64, v65
	v_mul_f32_e32 v64, 0xbfb8aa3b, v64
	v_mul_f32_e32 v73, v72, v73
	v_mul_f32_e32 v72, 0xbfb8aa3b, v72
	v_exp_f32_e32 v66, v66
	v_exp_f32_e32 v80, v80
	v_exp_f32_e32 v68, v68
	v_exp_f32_e32 v76, v76
	v_exp_f32_e32 v70, v70
	v_exp_f32_e32 v78, v78
	v_exp_f32_e32 v64, v64
	v_exp_f32_e32 v72, v72
	v_add_f32_e32 v66, 1.0, v66
	v_add_f32_e32 v80, 1.0, v80
	v_add_f32_e32 v68, 1.0, v68
	v_add_f32_e32 v76, 1.0, v76
	v_add_f32_e32 v70, 1.0, v70
	v_add_f32_e32 v78, 1.0, v78
	v_add_f32_e32 v64, 1.0, v64
; __device__ __forceinline__ float sigmoidf_(float x) { return __builtin_amdgcn_rcpf(1.f + __expf(-x)); }
;     __device__ __forceinline__ void operator()(const AccT& acc, const Unit& u, int wr, int wc, int fr, int fq) const {
;         const int row0 = u.pm * BM + wr * 64 + fr, col = u.pn * 128 + wc * 32 + 8 * fq;
; #pragma unroll
;         for (int ai = 0; ai < 2; ++ai)
; #pragma unroll
;             for (int m = 0; m < 4; ++m) {
;                 const int row = row0 + ai * HALF + m * 16;
;                 const float rs = rsqrtf(ss[row] * (1.f / 1024.f) + EPS);
;                 float o[8];
; #pragma unroll
;                 for (int n = 0; n < 2; ++n)
; #pragma unroll
;                     for (int j = 0; j < 4; ++j) { const float gt = acc[ai][0][m][n][j] * rs, up = acc[ai][1][m][n][j] * rs; o[n * 4 + j] = gt * up * sigmoidf_(gt); }
;                 *(u32x4*)(O + (size_t)row * FF + col) = pack8(o);
;             }
;     }
	v_add_f32_e32 v72, 1.0, v72
	v_rcp_f32_e32 v66, v66
	v_rcp_f32_e32 v80, v80
	v_rcp_f32_e32 v68, v68
	v_rcp_f32_e32 v76, v76
	v_rcp_f32_e32 v70, v70
	v_rcp_f32_e32 v78, v78
	v_rcp_f32_e32 v64, v64
	v_rcp_f32_e32 v72, v72
	v_mul_f32_e32 v67, v67, v66
	v_mul_f32_e32 v80, v81, v80
	v_mul_f32_e32 v68, v69, v68
	v_mul_f32_e32 v69, v77, v76
	v_mul_f32_e32 v70, v71, v70
	v_mul_f32_e32 v71, v79, v78
	v_mul_f32_e32 v76, v65, v64
	v_mul_f32_e32 v72, v73, v72
	v_cvt_pk_bf16_f32 v64, v80, v68
	v_cvt_pk_bf16_f32 v65, v69, v70
	v_cvt_pk_bf16_f32 v66, v71, v76
	v_cvt_pk_bf16_f32 v67, v72, v67
	global_store_dwordx4 v[74:75], v[64:67], off
	s_nop 0
	s_nop 0
	v_mov_b32_e32 v65, v52
	v_mov_b32_e32 v52, v61
	v_mov_b32_e32 v61, v54
	v_mov_b32_e32 v54, v63
	v_mov_b32_e32 v63, v48
	v_mov_b32_e32 v48, v57
	v_mov_b32_e32 v57, v50
	v_mov_b32_e32 v50, v59
	v_mov_b32_e32 v64, v60
	v_mov_b32_e32 v60, v62
	v_mov_b32_e32 v62, v56
	v_mov_b32_e32 v56, v58
	v_add_u32_e32 v58, 0x80, v146
	s_nop 0
	v_fmamk_f32 v59, v236, 0x3a800000, v155
	v_mul_f32_e32 v66, 0x4b800000, v59
	v_cmp_gt_f32_e32 vcc, s78, v59
	s_nop 1
	v_cndmask_b32_e32 v59, v59, v66, vcc
	v_rsq_f32_e32 v66, v59
	v_mad_i64_i32 v[58:59], s[4:5], v58, s79, v[120:121]
	v_lshl_add_u64 v[58:59], v[58:59], 0, v[122:123]
	v_mul_f32_e32 v67, 0x45800000, v66
	v_cndmask_b32_e32 v66, v66, v67, vcc
	v_pk_mul_f32 v[50:51], v[50:51], v[66:67] op_sel_hi:[1,0]
	v_pk_mul_f32 v[64:65], v[64:65], v[66:67] op_sel_hi:[1,0]
	v_pk_mul_f32 v[52:53], v[52:53], v[66:67] op_sel_hi:[1,0]
	v_pk_mul_f32 v[60:61], v[60:61], v[66:67] op_sel_hi:[1,0]
	v_pk_mul_f32 v[54:55], v[54:55], v[66:67] op_sel_hi:[1,0]
	v_pk_mul_f32 v[62:63], v[62:63], v[66:67] op_sel_hi:[1,0]
	v_pk_mul_f32 v[48:49], v[48:49], v[66:67] op_sel_hi:[1,0]
	v_pk_mul_f32 v[56:57], v[56:57], v[66:67] op_sel_hi:[1,0]
	v_mul_f32_e32 v51, v50, v51
	v_mul_f32_e32 v50, 0xbfb8aa3b, v50
	v_mul_f32_e32 v65, v64, v65
	v_mul_f32_e32 v64, 0xbfb8aa3b, v64
	v_mul_f32_e32 v53, v52, v53
	v_mul_f32_e32 v52, 0xbfb8aa3b, v52
	v_mul_f32_e32 v61, v60, v61
	v_mul_f32_e32 v60, 0xbfb8aa3b, v60
	v_mul_f32_e32 v55, v54, v55
	v_mul_f32_e32 v54, 0xbfb8aa3b, v54
	v_mul_f32_e32 v63, v62, v63
	v_mul_f32_e32 v62, 0xbfb8aa3b, v62
	v_mul_f32_e32 v49, v48, v49
	v_mul_f32_e32 v48, 0xbfb8aa3b, v48
	v_mul_f32_e32 v57, v56, v57
	v_mul_f32_e32 v56, 0xbfb8aa3b, v56
	v_exp_f32_e32 v50, v50
	v_exp_f32_e32 v64, v64
	v_exp_f32_e32 v52, v52
	v_exp_f32_e32 v60, v60
	v_exp_f32_e32 v54, v54
	v_exp_f32_e32 v62, v62
	v_exp_f32_e32 v48, v48
	v_exp_f32_e32 v56, v56
	v_add_f32_e32 v50, 1.0, v50
	v_add_f32_e32 v64, 1.0, v64
	v_add_f32_e32 v52, 1.0, v52
	v_add_f32_e32 v60, 1.0, v60
	v_add_f32_e32 v54, 1.0, v54
	v_add_f32_e32 v62, 1.0, v62
	v_add_f32_e32 v48, 1.0, v48
	v_add_f32_e32 v56, 1.0, v56
	v_rcp_f32_e32 v50, v50
	v_rcp_f32_e32 v64, v64
	v_rcp_f32_e32 v52, v52
	v_rcp_f32_e32 v60, v60
	v_rcp_f32_e32 v54, v54
	v_rcp_f32_e32 v62, v62
	v_rcp_f32_e32 v48, v48
	v_rcp_f32_e32 v56, v56
	v_mul_f32_e32 v51, v51, v50
	v_mul_f32_e32 v64, v65, v64
	v_mul_f32_e32 v52, v53, v52
	v_mul_f32_e32 v53, v61, v60
	v_mul_f32_e32 v54, v55, v54
	v_mul_f32_e32 v55, v63, v62
	v_mul_f32_e32 v60, v49, v48
	v_mul_f32_e32 v56, v57, v56
	v_cvt_pk_bf16_f32 v48, v64, v52
	v_cvt_pk_bf16_f32 v49, v53, v54
	v_cvt_pk_bf16_f32 v50, v55, v60
	v_cvt_pk_bf16_f32 v51, v56, v51
	global_store_dwordx4 v[58:59], v[48:51], off
	s_nop 0
	s_nop 0
	v_mov_b32_e32 v49, v36
	v_mov_b32_e32 v36, v45
	v_mov_b32_e32 v45, v38
	v_mov_b32_e32 v38, v47
	v_mov_b32_e32 v47, v32
	v_mov_b32_e32 v32, v41
	v_mov_b32_e32 v41, v34
	v_mov_b32_e32 v34, v43
	v_mov_b32_e32 v48, v44
	v_mov_b32_e32 v44, v46
	v_mov_b32_e32 v46, v40
	v_mov_b32_e32 v40, v42
	v_add_u32_e32 v42, 0x90, v146
	s_nop 0
	v_fmamk_f32 v43, v237, 0x3a800000, v155
	v_mul_f32_e32 v50, 0x4b800000, v43
	v_cmp_gt_f32_e32 vcc, s78, v43
	s_nop 1
	v_cndmask_b32_e32 v43, v43, v50, vcc
	v_rsq_f32_e32 v50, v43
	v_mad_i64_i32 v[42:43], s[4:5], v42, s79, v[120:121]
	v_lshl_add_u64 v[42:43], v[42:43], 0, v[122:123]
	v_mul_f32_e32 v51, 0x45800000, v50
	v_cndmask_b32_e32 v50, v50, v51, vcc
	v_pk_mul_f32 v[34:35], v[34:35], v[50:51] op_sel_hi:[1,0]
	v_pk_mul_f32 v[48:49], v[48:49], v[50:51] op_sel_hi:[1,0]
	v_pk_mul_f32 v[36:37], v[36:37], v[50:51] op_sel_hi:[1,0]
	v_pk_mul_f32 v[44:45], v[44:45], v[50:51] op_sel_hi:[1,0]
	v_pk_mul_f32 v[38:39], v[38:39], v[50:51] op_sel_hi:[1,0]
	v_pk_mul_f32 v[46:47], v[46:47], v[50:51] op_sel_hi:[1,0]
	v_pk_mul_f32 v[32:33], v[32:33], v[50:51] op_sel_hi:[1,0]
	v_pk_mul_f32 v[40:41], v[40:41], v[50:51] op_sel_hi:[1,0]
	v_mul_f32_e32 v35, v34, v35
	v_mul_f32_e32 v34, 0xbfb8aa3b, v34
	v_mul_f32_e32 v49, v48, v49
	v_mul_f32_e32 v48, 0xbfb8aa3b, v48
	v_mul_f32_e32 v37, v36, v37
	v_mul_f32_e32 v36, 0xbfb8aa3b, v36
	v_mul_f32_e32 v45, v44, v45
	v_mul_f32_e32 v44, 0xbfb8aa3b, v44
	v_mul_f32_e32 v39, v38, v39
	v_mul_f32_e32 v38, 0xbfb8aa3b, v38
	v_mul_f32_e32 v47, v46, v47
	v_mul_f32_e32 v46, 0xbfb8aa3b, v46
	v_mul_f32_e32 v33, v32, v33
	v_mul_f32_e32 v32, 0xbfb8aa3b, v32
	v_mul_f32_e32 v41, v40, v41
	v_mul_f32_e32 v40, 0xbfb8aa3b, v40
	v_exp_f32_e32 v34, v34
	v_exp_f32_e32 v48, v48
	v_exp_f32_e32 v36, v36
	v_exp_f32_e32 v44, v44
	v_exp_f32_e32 v38, v38
	v_exp_f32_e32 v46, v46
	v_exp_f32_e32 v32, v32
	v_exp_f32_e32 v40, v40
	v_add_f32_e32 v34, 1.0, v34
	v_add_f32_e32 v48, 1.0, v48
	v_add_f32_e32 v36, 1.0, v36
	v_add_f32_e32 v44, 1.0, v44
	v_add_f32_e32 v38, 1.0, v38
	v_add_f32_e32 v46, 1.0, v46
	v_add_f32_e32 v32, 1.0, v32
	v_add_f32_e32 v40, 1.0, v40
	v_rcp_f32_e32 v34, v34
	v_rcp_f32_e32 v48, v48
	v_rcp_f32_e32 v36, v36
	v_rcp_f32_e32 v44, v44
	v_rcp_f32_e32 v38, v38
	v_rcp_f32_e32 v46, v46
	v_rcp_f32_e32 v32, v32
; __device__ __forceinline__ float sigmoidf_(float x) { return __builtin_amdgcn_rcpf(1.f + __expf(-x)); }
;     __device__ __forceinline__ void operator()(const AccT& acc, const Unit& u, int wr, int wc, int fr, int fq) const {
;         const int row0 = u.pm * BM + wr * 64 + fr, col = u.pn * 128 + wc * 32 + 8 * fq;
; #pragma unroll
;         for (int ai = 0; ai < 2; ++ai)
; #pragma unroll
;             for (int m = 0; m < 4; ++m) {
;                 const int row = row0 + ai * HALF + m * 16;
;                 const float rs = rsqrtf(ss[row] * (1.f / 1024.f) + EPS);
;                 float o[8];
; #pragma unroll
;                 for (int n = 0; n < 2; ++n)
; #pragma unroll
;                     for (int j = 0; j < 4; ++j) { const float gt = acc[ai][0][m][n][j] * rs, up = acc[ai][1][m][n][j] * rs; o[n * 4 + j] = gt * up * sigmoidf_(gt); }
;                 *(u32x4*)(O + (size_t)row * FF + col) = pack8(o);
;             }
;     }
	v_rcp_f32_e32 v40, v40
	v_mul_f32_e32 v35, v35, v34
	v_mul_f32_e32 v48, v49, v48
	v_mul_f32_e32 v36, v37, v36
	v_mul_f32_e32 v37, v45, v44
	v_mul_f32_e32 v38, v39, v38
	v_mul_f32_e32 v39, v47, v46
	v_mul_f32_e32 v44, v33, v32
	v_mul_f32_e32 v40, v41, v40
	v_cvt_pk_bf16_f32 v32, v48, v36
	v_cvt_pk_bf16_f32 v33, v37, v38
	v_cvt_pk_bf16_f32 v34, v39, v44
	v_cvt_pk_bf16_f32 v35, v40, v35
	global_store_dwordx4 v[42:43], v[32:35], off
	s_nop 0
	s_nop 0
	v_mov_b32_e32 v33, v20
	v_mov_b32_e32 v20, v29
	v_mov_b32_e32 v29, v22
	v_mov_b32_e32 v22, v31
	v_mov_b32_e32 v31, v16
	v_mov_b32_e32 v16, v25
	v_mov_b32_e32 v25, v18
	v_mov_b32_e32 v18, v27
	v_mov_b32_e32 v32, v28
	v_mov_b32_e32 v28, v30
	v_mov_b32_e32 v30, v24
	v_mov_b32_e32 v24, v26
	v_add_u32_e32 v26, 0xa0, v146
	s_nop 0
	v_fmamk_f32 v27, v238, 0x3a800000, v155
	v_mul_f32_e32 v34, 0x4b800000, v27
	v_cmp_gt_f32_e32 vcc, s78, v27
	s_nop 1
	v_cndmask_b32_e32 v27, v27, v34, vcc
	v_rsq_f32_e32 v34, v27
	v_mad_i64_i32 v[26:27], s[4:5], v26, s79, v[120:121]
	v_lshl_add_u64 v[26:27], v[26:27], 0, v[122:123]
	v_mul_f32_e32 v35, 0x45800000, v34
	v_cndmask_b32_e32 v34, v34, v35, vcc
	v_pk_mul_f32 v[18:19], v[18:19], v[34:35] op_sel_hi:[1,0]
	v_pk_mul_f32 v[32:33], v[32:33], v[34:35] op_sel_hi:[1,0]
	v_pk_mul_f32 v[20:21], v[20:21], v[34:35] op_sel_hi:[1,0]
	v_pk_mul_f32 v[28:29], v[28:29], v[34:35] op_sel_hi:[1,0]
	v_pk_mul_f32 v[22:23], v[22:23], v[34:35] op_sel_hi:[1,0]
	v_pk_mul_f32 v[30:31], v[30:31], v[34:35] op_sel_hi:[1,0]
	v_pk_mul_f32 v[16:17], v[16:17], v[34:35] op_sel_hi:[1,0]
	v_pk_mul_f32 v[24:25], v[24:25], v[34:35] op_sel_hi:[1,0]
	v_mul_f32_e32 v19, v18, v19
	v_mul_f32_e32 v18, 0xbfb8aa3b, v18
	v_mul_f32_e32 v33, v32, v33
	v_mul_f32_e32 v32, 0xbfb8aa3b, v32
	v_mul_f32_e32 v21, v20, v21
	v_mul_f32_e32 v20, 0xbfb8aa3b, v20
	v_mul_f32_e32 v29, v28, v29
	v_mul_f32_e32 v28, 0xbfb8aa3b, v28
	v_mul_f32_e32 v23, v22, v23
	v_mul_f32_e32 v22, 0xbfb8aa3b, v22
	v_mul_f32_e32 v31, v30, v31
	v_mul_f32_e32 v30, 0xbfb8aa3b, v30
	v_mul_f32_e32 v17, v16, v17
	v_mul_f32_e32 v16, 0xbfb8aa3b, v16
	v_mul_f32_e32 v25, v24, v25
	v_mul_f32_e32 v24, 0xbfb8aa3b, v24
	v_exp_f32_e32 v18, v18
	v_exp_f32_e32 v32, v32
	v_exp_f32_e32 v20, v20
	v_exp_f32_e32 v28, v28
	v_exp_f32_e32 v22, v22
	v_exp_f32_e32 v30, v30
	v_exp_f32_e32 v16, v16
	v_exp_f32_e32 v24, v24
	v_add_f32_e32 v18, 1.0, v18
	v_add_f32_e32 v32, 1.0, v32
	v_add_f32_e32 v20, 1.0, v20
	v_add_f32_e32 v28, 1.0, v28
	v_add_f32_e32 v22, 1.0, v22
	v_add_f32_e32 v30, 1.0, v30
	v_add_f32_e32 v16, 1.0, v16
	v_add_f32_e32 v24, 1.0, v24
	v_rcp_f32_e32 v18, v18
	v_rcp_f32_e32 v32, v32
	v_rcp_f32_e32 v20, v20
	v_rcp_f32_e32 v28, v28
	v_rcp_f32_e32 v22, v22
	v_rcp_f32_e32 v30, v30
	v_rcp_f32_e32 v16, v16
	v_rcp_f32_e32 v24, v24
	v_mul_f32_e32 v19, v19, v18
	v_mul_f32_e32 v32, v33, v32
	v_mul_f32_e32 v20, v21, v20
	v_mul_f32_e32 v21, v29, v28
	v_mul_f32_e32 v22, v23, v22
	v_mul_f32_e32 v23, v31, v30
	v_mul_f32_e32 v28, v17, v16
	v_mul_f32_e32 v24, v25, v24
	v_cvt_pk_bf16_f32 v16, v32, v20
	v_cvt_pk_bf16_f32 v17, v21, v22
	v_cvt_pk_bf16_f32 v18, v23, v28
	v_cvt_pk_bf16_f32 v19, v24, v19
	global_store_dwordx4 v[26:27], v[16:19], off
	s_nop 0
	s_andn2_b64 vcc, exec, s[0:1]
	v_mov_b32_e32 v17, v4
	v_mov_b32_e32 v4, v13
	v_mov_b32_e32 v13, v6
	v_mov_b32_e32 v6, v15
	v_mov_b32_e32 v15, v0
	v_mov_b32_e32 v0, v9
	v_mov_b32_e32 v9, v2
	v_mov_b32_e32 v2, v11
	v_mov_b32_e32 v16, v12
	v_mov_b32_e32 v12, v14
	v_mov_b32_e32 v14, v8
	v_mov_b32_e32 v8, v10
	v_add_u32_e32 v10, 0xb0, v146
	s_mov_b64 s[0:1], -1
	s_nop 0
	v_fmamk_f32 v11, v239, 0x3a800000, v155
	v_mul_f32_e32 v18, 0x4b800000, v11
	v_cmp_gt_f32_e64 s[4:5], s78, v11
	s_nop 1
	v_cndmask_b32_e64 v11, v11, v18, s[4:5]
	v_rsq_f32_e32 v18, v11
	v_mad_i64_i32 v[10:11], s[22:23], v10, s79, v[120:121]
	v_lshl_add_u64 v[10:11], v[10:11], 0, v[122:123]
	v_mul_f32_e32 v19, 0x45800000, v18
	v_cndmask_b32_e64 v18, v18, v19, s[4:5]
	v_pk_mul_f32 v[2:3], v[2:3], v[18:19] op_sel_hi:[1,0]
	v_pk_mul_f32 v[16:17], v[16:17], v[18:19] op_sel_hi:[1,0]
	v_pk_mul_f32 v[4:5], v[4:5], v[18:19] op_sel_hi:[1,0]
	v_pk_mul_f32 v[12:13], v[12:13], v[18:19] op_sel_hi:[1,0]
	v_pk_mul_f32 v[6:7], v[6:7], v[18:19] op_sel_hi:[1,0]
	v_pk_mul_f32 v[14:15], v[14:15], v[18:19] op_sel_hi:[1,0]
	v_pk_mul_f32 v[0:1], v[0:1], v[18:19] op_sel_hi:[1,0]
	v_pk_mul_f32 v[8:9], v[8:9], v[18:19] op_sel_hi:[1,0]
	v_mul_f32_e32 v3, v2, v3
	v_mul_f32_e32 v2, 0xbfb8aa3b, v2
	v_mul_f32_e32 v17, v16, v17
	v_mul_f32_e32 v16, 0xbfb8aa3b, v16
	v_mul_f32_e32 v5, v4, v5
	v_mul_f32_e32 v4, 0xbfb8aa3b, v4
	v_mul_f32_e32 v13, v12, v13
	v_mul_f32_e32 v12, 0xbfb8aa3b, v12
	v_mul_f32_e32 v7, v6, v7
	v_mul_f32_e32 v6, 0xbfb8aa3b, v6
	v_mul_f32_e32 v15, v14, v15
	v_mul_f32_e32 v14, 0xbfb8aa3b, v14
	v_mul_f32_e32 v1, v0, v1
	v_mul_f32_e32 v0, 0xbfb8aa3b, v0
	v_mul_f32_e32 v9, v8, v9
	v_mul_f32_e32 v8, 0xbfb8aa3b, v8
	v_exp_f32_e32 v2, v2
	v_exp_f32_e32 v16, v16
	v_exp_f32_e32 v4, v4
	v_exp_f32_e32 v12, v12
	v_exp_f32_e32 v6, v6
	v_exp_f32_e32 v14, v14
	v_exp_f32_e32 v0, v0
	v_exp_f32_e32 v8, v8
	v_add_f32_e32 v2, 1.0, v2
	v_add_f32_e32 v16, 1.0, v16
	v_add_f32_e32 v4, 1.0, v4
	v_add_f32_e32 v12, 1.0, v12
	v_add_f32_e32 v6, 1.0, v6
	v_add_f32_e32 v14, 1.0, v14
	v_add_f32_e32 v0, 1.0, v0
	v_add_f32_e32 v8, 1.0, v8
	v_rcp_f32_e32 v2, v2
	v_rcp_f32_e32 v16, v16
	v_rcp_f32_e32 v4, v4
	v_rcp_f32_e32 v12, v12
	v_rcp_f32_e32 v6, v6
	v_rcp_f32_e32 v14, v14
	v_rcp_f32_e32 v0, v0
	v_rcp_f32_e32 v8, v8
	v_mul_f32_e32 v3, v3, v2
	v_mul_f32_e32 v16, v17, v16
	v_mul_f32_e32 v4, v5, v4
	v_mul_f32_e32 v5, v13, v12
	v_mul_f32_e32 v6, v7, v6
	v_mul_f32_e32 v7, v15, v14
	v_mul_f32_e32 v12, v1, v0
	v_mul_f32_e32 v8, v9, v8
	v_cvt_pk_bf16_f32 v0, v16, v4
	v_cvt_pk_bf16_f32 v1, v5, v6
	v_cvt_pk_bf16_f32 v2, v7, v12
	v_cvt_pk_bf16_f32 v3, v8, v3
	global_store_dwordx4 v[10:11], v[0:3], off
	s_cbranch_vccnz .LBB0_219
	s_andn2_b64 vcc, exec, s[6:7]
	s_cbranch_vccnz .LBB0_218
	s_barrier
	s_branch .LBB0_218

; __device__ __forceinline__ float sigmoidf_(float x) { return __builtin_amdgcn_rcpf(1.f + __expf(-x)); }
;     __device__ __forceinline__ void operator()(const AccT& acc, const Unit& u, int wr, int wc, int fr, int fq) const {
;         const int row0 = u.pm * BM + wr * 64 + fr, col = u.pn * 128 + wc * 32 + 8 * fq;
; #pragma unroll
;         for (int ai = 0; ai < 2; ++ai)
; #pragma unroll
;             for (int m = 0; m < 4; ++m) {
;                 const int row = row0 + ai * HALF + m * 16;
;                 const float rs = rsqrtf(ss[row] * (1.f / 1024.f) + EPS);
;                 float o[8];
; #pragma unroll
;                 for (int n = 0; n < 2; ++n)
; #pragma unroll
;                     for (int j = 0; j < 4; ++j) { const float gt = acc[ai][0][m][n][j] * rs, up = acc[ai][1][m][n][j] * rs; o[n * 4 + j] = gt * up * sigmoidf_(gt); }
;                 *(u32x4*)(O + (size_t)row * FF + col) = pack8(o);
;             }
;     }
.LBB0_1561:
	v_lshl_add_u32 v144, s0, 8, v148
	v_ashrrev_i32_e32 v145, 31, v144
	v_lshl_add_u64 v[146:147], v[144:145], 2, s[8:9]
	global_load_dword v145, v[146:147], off
	global_load_dword v233, v[146:147], off offset:64
	global_load_dword v234, v[146:147], off offset:128
	global_load_dword v235, v[146:147], off offset:192
	global_load_dword v236, v[146:147], off offset:512
	global_load_dword v237, v[146:147], off offset:576
	global_load_dword v238, v[146:147], off offset:640
	global_load_dword v239, v[146:147], off offset:704
	v_mov_b32_e32 v163, v114
	v_mov_b32_e32 v114, v123
	v_mov_b32_e32 v160, v124
	v_mov_b32_e32 v161, v116
	v_mov_b32_e32 v116, v125
	v_mov_b32_e32 v124, v126
	v_mov_b32_e32 v125, v118
	v_mov_b32_e32 v118, v127
	v_mov_b32_e32 v126, v120
	v_mov_b32_e32 v127, v112
	v_mov_b32_e32 v112, v121
	v_mov_b32_e32 v162, v122
	v_lshl_or_b32 v158, s1, 7, v150
	v_mov_b64_e32 v[120:121], s[44:45]
	v_ashrrev_i32_e32 v159, 31, v158
	v_mad_i64_i32 v[164:165], s[0:1], v144, s55, v[120:121]
	v_or_b32_e32 v166, 16, v144
	v_lshlrev_b64 v[122:123], 1, v[158:159]
	v_ashrrev_i32_e32 v167, 31, v166
	v_lshl_add_u64 v[158:159], v[164:165], 0, v[122:123]
	v_lshl_add_u64 v[164:165], v[166:167], 2, s[8:9]
	s_waitcnt vmcnt(0)
	v_fmamk_f32 v145, v145, 0x3a800000, v154
	v_mul_f32_e32 v155, 0x4b800000, v145
	v_cmp_gt_f32_e32 vcc, s54, v145
	s_nop 1
	v_cndmask_b32_e32 v145, v145, v155, vcc
	v_rsq_f32_e32 v145, v145
	s_nop 0
	v_mul_f32_e32 v155, 0x45800000, v145
	v_cndmask_b32_e32 v168, v145, v155, vcc
	v_pk_mul_f32 v[114:115], v[114:115], v[168:169] op_sel_hi:[1,0]
	v_pk_mul_f32 v[160:161], v[160:161], v[168:169] op_sel_hi:[1,0]
	v_pk_mul_f32 v[116:117], v[116:117], v[168:169] op_sel_hi:[1,0]
	v_pk_mul_f32 v[124:125], v[124:125], v[168:169] op_sel_hi:[1,0]
	v_pk_mul_f32 v[118:119], v[118:119], v[168:169] op_sel_hi:[1,0]
	v_pk_mul_f32 v[126:127], v[126:127], v[168:169] op_sel_hi:[1,0]
	v_pk_mul_f32 v[112:113], v[112:113], v[168:169] op_sel_hi:[1,0]
	v_pk_mul_f32 v[162:163], v[162:163], v[168:169] op_sel_hi:[1,0]
	v_mul_f32_e32 v115, v114, v115
	v_mul_f32_e32 v114, 0xbfb8aa3b, v114
	v_mul_f32_e32 v145, v160, v161
	v_mul_f32_e32 v155, 0xbfb8aa3b, v160
	v_mul_f32_e32 v117, v116, v117
	v_mul_f32_e32 v116, 0xbfb8aa3b, v116
	v_mul_f32_e32 v125, v124, v125
	v_mul_f32_e32 v124, 0xbfb8aa3b, v124
	v_mul_f32_e32 v119, v118, v119
	v_mul_f32_e32 v118, 0xbfb8aa3b, v118
	v_mul_f32_e32 v127, v126, v127
	v_mul_f32_e32 v126, 0xbfb8aa3b, v126
	v_mul_f32_e32 v113, v112, v113
	v_mul_f32_e32 v112, 0xbfb8aa3b, v112
	v_mul_f32_e32 v160, 0xbfb8aa3b, v162
	v_exp_f32_e32 v114, v114
	v_exp_f32_e32 v155, v155
	v_exp_f32_e32 v116, v116
	v_exp_f32_e32 v124, v124
	v_exp_f32_e32 v118, v118
	v_exp_f32_e32 v126, v126
	v_exp_f32_e32 v112, v112
	v_exp_f32_e32 v160, v160
	v_add_f32_e32 v114, 1.0, v114
	v_add_f32_e32 v155, 1.0, v155
	v_add_f32_e32 v116, 1.0, v116
	v_add_f32_e32 v124, 1.0, v124
	v_add_f32_e32 v118, 1.0, v118
	v_add_f32_e32 v126, 1.0, v126
	v_add_f32_e32 v112, 1.0, v112
	v_add_f32_e32 v160, 1.0, v160
	v_rcp_f32_e32 v114, v114
	v_rcp_f32_e32 v155, v155
	v_rcp_f32_e32 v116, v116
	v_rcp_f32_e32 v124, v124
	v_rcp_f32_e32 v118, v118
	v_rcp_f32_e32 v126, v126
	v_rcp_f32_e32 v112, v112
	v_rcp_f32_e32 v160, v160
	v_mul_f32_e32 v157, v162, v163
	v_mul_f32_e32 v115, v115, v114
	v_mul_f32_e32 v145, v145, v155
	v_mul_f32_e32 v116, v117, v116
	v_mul_f32_e32 v117, v125, v124
	v_mul_f32_e32 v118, v119, v118
	v_mul_f32_e32 v119, v127, v126
	v_mul_f32_e32 v124, v113, v112
	v_mul_f32_e32 v125, v157, v160
	v_cvt_pk_bf16_f32 v112, v145, v116
	v_cvt_pk_bf16_f32 v113, v117, v118
	v_cvt_pk_bf16_f32 v114, v119, v124
	v_cvt_pk_bf16_f32 v115, v125, v115
	global_store_dwordx4 v[158:159], v[112:115], off
	s_nop 0
	s_nop 0
	v_mov_b32_e32 v113, v100
	v_mov_b32_e32 v100, v109
	v_mov_b32_e32 v109, v102
	v_mov_b32_e32 v102, v111
	v_mov_b32_e32 v111, v96
	v_mov_b32_e32 v96, v105
	v_mov_b32_e32 v105, v98
	v_mov_b32_e32 v98, v107
	v_mov_b32_e32 v112, v108
	v_mov_b32_e32 v108, v110
	v_mov_b32_e32 v110, v104
	v_mov_b32_e32 v104, v106
	v_or_b32_e32 v106, 32, v144
	v_mad_i64_i32 v[114:115], s[0:1], v166, s55, v[120:121]
	v_lshl_add_u64 v[114:115], v[114:115], 0, v[122:123]
	s_nop 0
	v_fmamk_f32 v107, v233, 0x3a800000, v154
	v_mul_f32_e32 v116, 0x4b800000, v107
	v_cmp_gt_f32_e32 vcc, s54, v107
	s_nop 1
	v_cndmask_b32_e32 v107, v107, v116, vcc
	v_rsq_f32_e32 v118, v107
	v_ashrrev_i32_e32 v107, 31, v106
	v_lshl_add_u64 v[116:117], v[106:107], 2, s[8:9]
	v_mul_f32_e32 v107, 0x45800000, v118
	v_cndmask_b32_e32 v118, v118, v107, vcc
	v_pk_mul_f32 v[98:99], v[98:99], v[118:119] op_sel_hi:[1,0]
	v_pk_mul_f32 v[112:113], v[112:113], v[118:119] op_sel_hi:[1,0]
	v_pk_mul_f32 v[100:101], v[100:101], v[118:119] op_sel_hi:[1,0]
	v_pk_mul_f32 v[108:109], v[108:109], v[118:119] op_sel_hi:[1,0]
	v_pk_mul_f32 v[102:103], v[102:103], v[118:119] op_sel_hi:[1,0]
	v_pk_mul_f32 v[110:111], v[110:111], v[118:119] op_sel_hi:[1,0]
	v_pk_mul_f32 v[96:97], v[96:97], v[118:119] op_sel_hi:[1,0]
	v_pk_mul_f32 v[104:105], v[104:105], v[118:119] op_sel_hi:[1,0]
	v_mul_f32_e32 v99, v98, v99
	v_mul_f32_e32 v98, 0xbfb8aa3b, v98
	v_mul_f32_e32 v107, v112, v113
	v_mul_f32_e32 v112, 0xbfb8aa3b, v112
	v_mul_f32_e32 v101, v100, v101
	v_mul_f32_e32 v100, 0xbfb8aa3b, v100
	v_mul_f32_e32 v109, v108, v109
	v_mul_f32_e32 v108, 0xbfb8aa3b, v108
	v_mul_f32_e32 v103, v102, v103
	v_mul_f32_e32 v102, 0xbfb8aa3b, v102
	v_mul_f32_e32 v111, v110, v111
	v_mul_f32_e32 v110, 0xbfb8aa3b, v110
	v_mul_f32_e32 v97, v96, v97
	v_mul_f32_e32 v96, 0xbfb8aa3b, v96
	v_mul_f32_e32 v105, v104, v105
	v_mul_f32_e32 v104, 0xbfb8aa3b, v104
	v_exp_f32_e32 v98, v98
	v_exp_f32_e32 v112, v112
; __device__ __forceinline__ float sigmoidf_(float x) { return __builtin_amdgcn_rcpf(1.f + __expf(-x)); }
;     __device__ __forceinline__ void operator()(const AccT& acc, const Unit& u, int wr, int wc, int fr, int fq) const {
;         const int row0 = u.pm * BM + wr * 64 + fr, col = u.pn * 128 + wc * 32 + 8 * fq;
; #pragma unroll
;         for (int ai = 0; ai < 2; ++ai)
; #pragma unroll
;             for (int m = 0; m < 4; ++m) {
;                 const int row = row0 + ai * HALF + m * 16;
;                 const float rs = rsqrtf(ss[row] * (1.f / 1024.f) + EPS);
;                 float o[8];
; #pragma unroll
;                 for (int n = 0; n < 2; ++n)
; #pragma unroll
;                     for (int j = 0; j < 4; ++j) { const float gt = acc[ai][0][m][n][j] * rs, up = acc[ai][1][m][n][j] * rs; o[n * 4 + j] = gt * up * sigmoidf_(gt); }
;                 *(u32x4*)(O + (size_t)row * FF + col) = pack8(o);
;             }
;     }
	v_exp_f32_e32 v100, v100
	v_exp_f32_e32 v108, v108
	v_exp_f32_e32 v102, v102
	v_exp_f32_e32 v110, v110
	v_exp_f32_e32 v96, v96
	v_exp_f32_e32 v104, v104
	v_add_f32_e32 v98, 1.0, v98
	v_add_f32_e32 v112, 1.0, v112
	v_add_f32_e32 v100, 1.0, v100
	v_add_f32_e32 v108, 1.0, v108
	v_add_f32_e32 v102, 1.0, v102
	v_add_f32_e32 v110, 1.0, v110
	v_add_f32_e32 v96, 1.0, v96
	v_add_f32_e32 v104, 1.0, v104
	v_rcp_f32_e32 v98, v98
	v_rcp_f32_e32 v112, v112
	v_rcp_f32_e32 v100, v100
	v_rcp_f32_e32 v108, v108
	v_rcp_f32_e32 v102, v102
	v_rcp_f32_e32 v110, v110
	v_rcp_f32_e32 v96, v96
	v_rcp_f32_e32 v104, v104
	v_mul_f32_e32 v99, v99, v98
	v_mul_f32_e32 v107, v107, v112
	v_mul_f32_e32 v100, v101, v100
	v_mul_f32_e32 v101, v109, v108
	v_mul_f32_e32 v102, v103, v102
	v_mul_f32_e32 v103, v111, v110
	v_mul_f32_e32 v108, v97, v96
	v_mul_f32_e32 v104, v105, v104
	v_cvt_pk_bf16_f32 v96, v107, v100
	v_cvt_pk_bf16_f32 v97, v101, v102
	v_cvt_pk_bf16_f32 v98, v103, v108
	v_cvt_pk_bf16_f32 v99, v104, v99
	global_store_dwordx4 v[114:115], v[96:99], off
	s_nop 0
	s_nop 0
	v_mov_b32_e32 v97, v84
	v_mov_b32_e32 v84, v93
	v_mov_b32_e32 v93, v86
	v_mov_b32_e32 v86, v95
	v_mov_b32_e32 v95, v80
	v_mov_b32_e32 v80, v89
	v_mov_b32_e32 v89, v82
	v_mov_b32_e32 v82, v91
	v_mov_b32_e32 v96, v92
	v_mov_b32_e32 v92, v94
	v_mov_b32_e32 v94, v88
	v_mov_b32_e32 v88, v90
	v_or_b32_e32 v90, 48, v144
	v_mad_i64_i32 v[98:99], s[0:1], v106, s55, v[120:121]
	v_lshl_add_u64 v[98:99], v[98:99], 0, v[122:123]
	s_nop 0
	v_fmamk_f32 v91, v234, 0x3a800000, v154
	v_mul_f32_e32 v100, 0x4b800000, v91
	v_cmp_gt_f32_e32 vcc, s54, v91
	s_nop 1
	v_cndmask_b32_e32 v91, v91, v100, vcc
	v_rsq_f32_e32 v102, v91
	v_ashrrev_i32_e32 v91, 31, v90
	v_lshl_add_u64 v[100:101], v[90:91], 2, s[8:9]
	v_mul_f32_e32 v91, 0x45800000, v102
	v_cndmask_b32_e32 v102, v102, v91, vcc
	v_pk_mul_f32 v[82:83], v[82:83], v[102:103] op_sel_hi:[1,0]
	v_pk_mul_f32 v[96:97], v[96:97], v[102:103] op_sel_hi:[1,0]
	v_pk_mul_f32 v[84:85], v[84:85], v[102:103] op_sel_hi:[1,0]
	v_pk_mul_f32 v[92:93], v[92:93], v[102:103] op_sel_hi:[1,0]
	v_pk_mul_f32 v[86:87], v[86:87], v[102:103] op_sel_hi:[1,0]
	v_pk_mul_f32 v[94:95], v[94:95], v[102:103] op_sel_hi:[1,0]
	v_pk_mul_f32 v[80:81], v[80:81], v[102:103] op_sel_hi:[1,0]
	v_pk_mul_f32 v[88:89], v[88:89], v[102:103] op_sel_hi:[1,0]
	v_mul_f32_e32 v83, v82, v83
	v_mul_f32_e32 v82, 0xbfb8aa3b, v82
	v_mul_f32_e32 v91, v96, v97
	v_mul_f32_e32 v96, 0xbfb8aa3b, v96
	v_mul_f32_e32 v85, v84, v85
	v_mul_f32_e32 v84, 0xbfb8aa3b, v84
	v_mul_f32_e32 v93, v92, v93
	v_mul_f32_e32 v92, 0xbfb8aa3b, v92
	v_mul_f32_e32 v87, v86, v87
	v_mul_f32_e32 v86, 0xbfb8aa3b, v86
	v_mul_f32_e32 v95, v94, v95
	v_mul_f32_e32 v94, 0xbfb8aa3b, v94
	v_mul_f32_e32 v81, v80, v81
	v_mul_f32_e32 v80, 0xbfb8aa3b, v80
	v_mul_f32_e32 v89, v88, v89
	v_mul_f32_e32 v88, 0xbfb8aa3b, v88
	v_exp_f32_e32 v82, v82
	v_exp_f32_e32 v96, v96
	v_exp_f32_e32 v84, v84
	v_exp_f32_e32 v92, v92
	v_exp_f32_e32 v86, v86
	v_exp_f32_e32 v94, v94
	v_exp_f32_e32 v80, v80
	v_exp_f32_e32 v88, v88
	v_add_f32_e32 v82, 1.0, v82
	v_add_f32_e32 v96, 1.0, v96
	v_add_f32_e32 v84, 1.0, v84
	v_add_f32_e32 v92, 1.0, v92
	v_add_f32_e32 v86, 1.0, v86
	v_add_f32_e32 v94, 1.0, v94
	v_add_f32_e32 v80, 1.0, v80
	v_add_f32_e32 v88, 1.0, v88
	v_rcp_f32_e32 v82, v82
	v_rcp_f32_e32 v96, v96
	v_rcp_f32_e32 v84, v84
	v_rcp_f32_e32 v92, v92
	v_rcp_f32_e32 v86, v86
	v_rcp_f32_e32 v94, v94
	v_rcp_f32_e32 v80, v80
	v_rcp_f32_e32 v88, v88
	v_mul_f32_e32 v83, v83, v82
	v_mul_f32_e32 v91, v91, v96
	v_mul_f32_e32 v84, v85, v84
	v_mul_f32_e32 v85, v93, v92
	v_mul_f32_e32 v86, v87, v86
	v_mul_f32_e32 v87, v95, v94
	v_mul_f32_e32 v92, v81, v80
	v_mul_f32_e32 v88, v89, v88
	v_cvt_pk_bf16_f32 v80, v91, v84
	v_cvt_pk_bf16_f32 v81, v85, v86
	v_cvt_pk_bf16_f32 v82, v87, v92
	v_cvt_pk_bf16_f32 v83, v88, v83
	global_store_dwordx4 v[98:99], v[80:83], off
	s_nop 0
	s_nop 0
	v_mov_b32_e32 v80, v76
	v_mov_b32_e32 v76, v78
	v_mov_b32_e32 v78, v72
	v_mov_b32_e32 v72, v74
	v_mov_b32_e32 v81, v68
	v_mov_b32_e32 v68, v77
	v_mov_b32_e32 v77, v70
	v_mov_b32_e32 v70, v79
	v_mov_b32_e32 v79, v64
	v_mov_b32_e32 v64, v73
	v_mov_b32_e32 v73, v66
	v_mov_b32_e32 v66, v75
	s_nop 0
	v_fmamk_f32 v74, v235, 0x3a800000, v154
	v_mul_f32_e32 v75, 0x4b800000, v74
	v_cmp_gt_f32_e32 vcc, s54, v74
	s_nop 1
	v_cndmask_b32_e32 v74, v74, v75, vcc
	v_rsq_f32_e32 v82, v74
	v_mad_i64_i32 v[74:75], s[0:1], v90, s55, v[120:121]
	v_lshl_add_u64 v[74:75], v[74:75], 0, v[122:123]
	v_mul_f32_e32 v83, 0x45800000, v82
	v_cndmask_b32_e32 v82, v82, v83, vcc
	v_pk_mul_f32 v[66:67], v[66:67], v[82:83] op_sel_hi:[1,0]
	v_pk_mul_f32 v[80:81], v[80:81], v[82:83] op_sel_hi:[1,0]
	v_pk_mul_f32 v[68:69], v[68:69], v[82:83] op_sel_hi:[1,0]
	v_pk_mul_f32 v[76:77], v[76:77], v[82:83] op_sel_hi:[1,0]
	v_pk_mul_f32 v[70:71], v[70:71], v[82:83] op_sel_hi:[1,0]
	v_pk_mul_f32 v[78:79], v[78:79], v[82:83] op_sel_hi:[1,0]
	v_pk_mul_f32 v[64:65], v[64:65], v[82:83] op_sel_hi:[1,0]
	v_pk_mul_f32 v[72:73], v[72:73], v[82:83] op_sel_hi:[1,0]
	v_mul_f32_e32 v67, v66, v67
	v_mul_f32_e32 v66, 0xbfb8aa3b, v66
	v_mul_f32_e32 v81, v80, v81
	v_mul_f32_e32 v80, 0xbfb8aa3b, v80
	v_mul_f32_e32 v69, v68, v69
	v_mul_f32_e32 v68, 0xbfb8aa3b, v68
	v_mul_f32_e32 v77, v76, v77
	v_mul_f32_e32 v76, 0xbfb8aa3b, v76
	v_mul_f32_e32 v71, v70, v71
	v_mul_f32_e32 v70, 0xbfb8aa3b, v70
	v_mul_f32_e32 v79, v78, v79
	v_mul_f32_e32 v78, 0xbfb8aa3b, v78
	v_mul_f32_e32 v65, v64, v65
	v_mul_f32_e32 v64, 0xbfb8aa3b, v64
	v_mul_f32_e32 v73, v72, v73
	v_mul_f32_e32 v72, 0xbfb8aa3b, v72
	v_exp_f32_e32 v66, v66
	v_exp_f32_e32 v80, v80
	v_exp_f32_e32 v68, v68
	v_exp_f32_e32 v76, v76
	v_exp_f32_e32 v70, v70
; __device__ __forceinline__ float sigmoidf_(float x) { return __builtin_amdgcn_rcpf(1.f + __expf(-x)); }
;     __device__ __forceinline__ void operator()(const AccT& acc, const Unit& u, int wr, int wc, int fr, int fq) const {
;         const int row0 = u.pm * BM + wr * 64 + fr, col = u.pn * 128 + wc * 32 + 8 * fq;
; #pragma unroll
;         for (int ai = 0; ai < 2; ++ai)
; #pragma unroll
;             for (int m = 0; m < 4; ++m) {
;                 const int row = row0 + ai * HALF + m * 16;
;                 const float rs = rsqrtf(ss[row] * (1.f / 1024.f) + EPS);
;                 float o[8];
; #pragma unroll
;                 for (int n = 0; n < 2; ++n)
; #pragma unroll
;                     for (int j = 0; j < 4; ++j) { const float gt = acc[ai][0][m][n][j] * rs, up = acc[ai][1][m][n][j] * rs; o[n * 4 + j] = gt * up * sigmoidf_(gt); }
;                 *(u32x4*)(O + (size_t)row * FF + col) = pack8(o);
;             }
;     }
	v_exp_f32_e32 v78, v78
	v_exp_f32_e32 v64, v64
	v_exp_f32_e32 v72, v72
	v_add_f32_e32 v66, 1.0, v66
	v_add_f32_e32 v80, 1.0, v80
	v_add_f32_e32 v68, 1.0, v68
	v_add_f32_e32 v76, 1.0, v76
	v_add_f32_e32 v70, 1.0, v70
	v_add_f32_e32 v78, 1.0, v78
	v_add_f32_e32 v64, 1.0, v64
	v_add_f32_e32 v72, 1.0, v72
	v_rcp_f32_e32 v66, v66
	v_rcp_f32_e32 v80, v80
	v_rcp_f32_e32 v68, v68
	v_rcp_f32_e32 v76, v76
	v_rcp_f32_e32 v70, v70
	v_rcp_f32_e32 v78, v78
	v_rcp_f32_e32 v64, v64
	v_rcp_f32_e32 v72, v72
	v_mul_f32_e32 v67, v67, v66
	v_mul_f32_e32 v80, v81, v80
	v_mul_f32_e32 v68, v69, v68
	v_mul_f32_e32 v69, v77, v76
	v_mul_f32_e32 v70, v71, v70
	v_mul_f32_e32 v71, v79, v78
	v_mul_f32_e32 v76, v65, v64
	v_mul_f32_e32 v72, v73, v72
	v_cvt_pk_bf16_f32 v64, v80, v68
	v_cvt_pk_bf16_f32 v65, v69, v70
	v_cvt_pk_bf16_f32 v66, v71, v76
	v_cvt_pk_bf16_f32 v67, v72, v67
	global_store_dwordx4 v[74:75], v[64:67], off
	s_nop 0
	s_nop 0
	v_mov_b32_e32 v65, v52
	v_mov_b32_e32 v52, v61
	v_mov_b32_e32 v61, v54
	v_mov_b32_e32 v54, v63
	v_mov_b32_e32 v63, v48
	v_mov_b32_e32 v48, v57
	v_mov_b32_e32 v57, v50
	v_mov_b32_e32 v50, v59
	v_mov_b32_e32 v64, v60
	v_mov_b32_e32 v60, v62
	v_mov_b32_e32 v62, v56
	v_mov_b32_e32 v56, v58
	v_add_u32_e32 v58, 0x80, v144
	s_nop 0
	v_fmamk_f32 v59, v236, 0x3a800000, v154
	v_mul_f32_e32 v66, 0x4b800000, v59
	v_cmp_gt_f32_e32 vcc, s54, v59
	s_nop 1
	v_cndmask_b32_e32 v59, v59, v66, vcc
	v_rsq_f32_e32 v66, v59
	v_mad_i64_i32 v[58:59], s[0:1], v58, s55, v[120:121]
	v_lshl_add_u64 v[58:59], v[58:59], 0, v[122:123]
	v_mul_f32_e32 v67, 0x45800000, v66
	v_cndmask_b32_e32 v66, v66, v67, vcc
	v_pk_mul_f32 v[50:51], v[50:51], v[66:67] op_sel_hi:[1,0]
	v_pk_mul_f32 v[64:65], v[64:65], v[66:67] op_sel_hi:[1,0]
	v_pk_mul_f32 v[52:53], v[52:53], v[66:67] op_sel_hi:[1,0]
	v_pk_mul_f32 v[60:61], v[60:61], v[66:67] op_sel_hi:[1,0]
	v_pk_mul_f32 v[54:55], v[54:55], v[66:67] op_sel_hi:[1,0]
	v_pk_mul_f32 v[62:63], v[62:63], v[66:67] op_sel_hi:[1,0]
	v_pk_mul_f32 v[48:49], v[48:49], v[66:67] op_sel_hi:[1,0]
	v_pk_mul_f32 v[56:57], v[56:57], v[66:67] op_sel_hi:[1,0]
	v_mul_f32_e32 v51, v50, v51
	v_mul_f32_e32 v50, 0xbfb8aa3b, v50
	v_mul_f32_e32 v65, v64, v65
	v_mul_f32_e32 v64, 0xbfb8aa3b, v64
	v_mul_f32_e32 v53, v52, v53
	v_mul_f32_e32 v52, 0xbfb8aa3b, v52
	v_mul_f32_e32 v61, v60, v61
	v_mul_f32_e32 v60, 0xbfb8aa3b, v60
	v_mul_f32_e32 v55, v54, v55
	v_mul_f32_e32 v54, 0xbfb8aa3b, v54
	v_mul_f32_e32 v63, v62, v63
	v_mul_f32_e32 v62, 0xbfb8aa3b, v62
	v_mul_f32_e32 v49, v48, v49
	v_mul_f32_e32 v48, 0xbfb8aa3b, v48
	v_mul_f32_e32 v57, v56, v57
	v_mul_f32_e32 v56, 0xbfb8aa3b, v56
	v_exp_f32_e32 v50, v50
	v_exp_f32_e32 v64, v64
	v_exp_f32_e32 v52, v52
	v_exp_f32_e32 v60, v60
	v_exp_f32_e32 v54, v54
	v_exp_f32_e32 v62, v62
	v_exp_f32_e32 v48, v48
	v_exp_f32_e32 v56, v56
	v_add_f32_e32 v50, 1.0, v50
	v_add_f32_e32 v64, 1.0, v64
	v_add_f32_e32 v52, 1.0, v52
	v_add_f32_e32 v60, 1.0, v60
	v_add_f32_e32 v54, 1.0, v54
	v_add_f32_e32 v62, 1.0, v62
	v_add_f32_e32 v48, 1.0, v48
	v_add_f32_e32 v56, 1.0, v56
	v_rcp_f32_e32 v50, v50
	v_rcp_f32_e32 v64, v64
	v_rcp_f32_e32 v52, v52
	v_rcp_f32_e32 v60, v60
	v_rcp_f32_e32 v54, v54
	v_rcp_f32_e32 v62, v62
	v_rcp_f32_e32 v48, v48
	v_rcp_f32_e32 v56, v56
	v_mul_f32_e32 v51, v51, v50
	v_mul_f32_e32 v64, v65, v64
	v_mul_f32_e32 v52, v53, v52
	v_mul_f32_e32 v53, v61, v60
	v_mul_f32_e32 v54, v55, v54
	v_mul_f32_e32 v55, v63, v62
	v_mul_f32_e32 v60, v49, v48
	v_mul_f32_e32 v56, v57, v56
	v_cvt_pk_bf16_f32 v48, v64, v52
	v_cvt_pk_bf16_f32 v49, v53, v54
	v_cvt_pk_bf16_f32 v50, v55, v60
	v_cvt_pk_bf16_f32 v51, v56, v51
	global_store_dwordx4 v[58:59], v[48:51], off
	s_nop 0
	s_nop 0
	v_mov_b32_e32 v49, v36
	v_mov_b32_e32 v36, v45
	v_mov_b32_e32 v45, v38
	v_mov_b32_e32 v38, v47
	v_mov_b32_e32 v47, v32
	v_mov_b32_e32 v32, v41
	v_mov_b32_e32 v41, v34
	v_mov_b32_e32 v34, v43
	v_mov_b32_e32 v48, v44
	v_mov_b32_e32 v44, v46
	v_mov_b32_e32 v46, v40
	v_mov_b32_e32 v40, v42
	v_add_u32_e32 v42, 0x90, v144
	s_nop 0
	v_fmamk_f32 v43, v237, 0x3a800000, v154
	v_mul_f32_e32 v50, 0x4b800000, v43
	v_cmp_gt_f32_e32 vcc, s54, v43
	s_nop 1
	v_cndmask_b32_e32 v43, v43, v50, vcc
	v_rsq_f32_e32 v50, v43
	v_mad_i64_i32 v[42:43], s[0:1], v42, s55, v[120:121]
	v_lshl_add_u64 v[42:43], v[42:43], 0, v[122:123]
	v_mul_f32_e32 v51, 0x45800000, v50
	v_cndmask_b32_e32 v50, v50, v51, vcc
	v_pk_mul_f32 v[34:35], v[34:35], v[50:51] op_sel_hi:[1,0]
	v_pk_mul_f32 v[48:49], v[48:49], v[50:51] op_sel_hi:[1,0]
	v_pk_mul_f32 v[36:37], v[36:37], v[50:51] op_sel_hi:[1,0]
	v_pk_mul_f32 v[44:45], v[44:45], v[50:51] op_sel_hi:[1,0]
	v_pk_mul_f32 v[38:39], v[38:39], v[50:51] op_sel_hi:[1,0]
	v_pk_mul_f32 v[46:47], v[46:47], v[50:51] op_sel_hi:[1,0]
	v_pk_mul_f32 v[32:33], v[32:33], v[50:51] op_sel_hi:[1,0]
	v_pk_mul_f32 v[40:41], v[40:41], v[50:51] op_sel_hi:[1,0]
	v_mul_f32_e32 v35, v34, v35
	v_mul_f32_e32 v34, 0xbfb8aa3b, v34
	v_mul_f32_e32 v49, v48, v49
	v_mul_f32_e32 v48, 0xbfb8aa3b, v48
	v_mul_f32_e32 v37, v36, v37
	v_mul_f32_e32 v36, 0xbfb8aa3b, v36
	v_mul_f32_e32 v45, v44, v45
	v_mul_f32_e32 v44, 0xbfb8aa3b, v44
	v_mul_f32_e32 v39, v38, v39
	v_mul_f32_e32 v38, 0xbfb8aa3b, v38
	v_mul_f32_e32 v47, v46, v47
	v_mul_f32_e32 v46, 0xbfb8aa3b, v46
	v_mul_f32_e32 v33, v32, v33
	v_mul_f32_e32 v32, 0xbfb8aa3b, v32
	v_mul_f32_e32 v41, v40, v41
	v_mul_f32_e32 v40, 0xbfb8aa3b, v40
	v_exp_f32_e32 v34, v34
	v_exp_f32_e32 v48, v48
	v_exp_f32_e32 v36, v36
	v_exp_f32_e32 v44, v44
	v_exp_f32_e32 v38, v38
	v_exp_f32_e32 v46, v46
	v_exp_f32_e32 v32, v32
	v_exp_f32_e32 v40, v40
	v_add_f32_e32 v34, 1.0, v34
	v_add_f32_e32 v48, 1.0, v48
	v_add_f32_e32 v36, 1.0, v36
	v_add_f32_e32 v44, 1.0, v44
; __device__ __forceinline__ float sigmoidf_(float x) { return __builtin_amdgcn_rcpf(1.f + __expf(-x)); }
;     __device__ __forceinline__ void operator()(const AccT& acc, const Unit& u, int wr, int wc, int fr, int fq) const {
;         const int row0 = u.pm * BM + wr * 64 + fr, col = u.pn * 128 + wc * 32 + 8 * fq;
; #pragma unroll
;         for (int ai = 0; ai < 2; ++ai)
; #pragma unroll
;             for (int m = 0; m < 4; ++m) {
;                 const int row = row0 + ai * HALF + m * 16;
;                 const float rs = rsqrtf(ss[row] * (1.f / 1024.f) + EPS);
;                 float o[8];
; #pragma unroll
;                 for (int n = 0; n < 2; ++n)
; #pragma unroll
;                     for (int j = 0; j < 4; ++j) { const float gt = acc[ai][0][m][n][j] * rs, up = acc[ai][1][m][n][j] * rs; o[n * 4 + j] = gt * up * sigmoidf_(gt); }
;                 *(u32x4*)(O + (size_t)row * FF + col) = pack8(o);
;             }
;     }
	v_add_f32_e32 v38, 1.0, v38
	v_add_f32_e32 v46, 1.0, v46
	v_add_f32_e32 v32, 1.0, v32
	v_add_f32_e32 v40, 1.0, v40
	v_rcp_f32_e32 v34, v34
	v_rcp_f32_e32 v48, v48
	v_rcp_f32_e32 v36, v36
	v_rcp_f32_e32 v44, v44
	v_rcp_f32_e32 v38, v38
	v_rcp_f32_e32 v46, v46
	v_rcp_f32_e32 v32, v32
	v_rcp_f32_e32 v40, v40
	v_mul_f32_e32 v35, v35, v34
	v_mul_f32_e32 v48, v49, v48
	v_mul_f32_e32 v36, v37, v36
	v_mul_f32_e32 v37, v45, v44
	v_mul_f32_e32 v38, v39, v38
	v_mul_f32_e32 v39, v47, v46
	v_mul_f32_e32 v44, v33, v32
	v_mul_f32_e32 v40, v41, v40
	v_cvt_pk_bf16_f32 v32, v48, v36
	v_cvt_pk_bf16_f32 v33, v37, v38
	v_cvt_pk_bf16_f32 v34, v39, v44
	v_cvt_pk_bf16_f32 v35, v40, v35
	global_store_dwordx4 v[42:43], v[32:35], off
	s_nop 0
	s_nop 0
	v_mov_b32_e32 v33, v20
	v_mov_b32_e32 v20, v29
	v_mov_b32_e32 v29, v22
	v_mov_b32_e32 v22, v31
	v_mov_b32_e32 v31, v16
	v_mov_b32_e32 v16, v25
	v_mov_b32_e32 v25, v18
	v_mov_b32_e32 v18, v27
	v_mov_b32_e32 v32, v28
	v_mov_b32_e32 v28, v30
	v_mov_b32_e32 v30, v24
	v_mov_b32_e32 v24, v26
	v_add_u32_e32 v26, 0xa0, v144
	s_nop 0
	v_fmamk_f32 v27, v238, 0x3a800000, v154
	v_mul_f32_e32 v34, 0x4b800000, v27
	v_cmp_gt_f32_e32 vcc, s54, v27
	s_nop 1
	v_cndmask_b32_e32 v27, v27, v34, vcc
	v_rsq_f32_e32 v34, v27
	v_mad_i64_i32 v[26:27], s[0:1], v26, s55, v[120:121]
	v_lshl_add_u64 v[26:27], v[26:27], 0, v[122:123]
	v_mul_f32_e32 v35, 0x45800000, v34
	v_cndmask_b32_e32 v34, v34, v35, vcc
	v_pk_mul_f32 v[18:19], v[18:19], v[34:35] op_sel_hi:[1,0]
	v_pk_mul_f32 v[32:33], v[32:33], v[34:35] op_sel_hi:[1,0]
	v_pk_mul_f32 v[20:21], v[20:21], v[34:35] op_sel_hi:[1,0]
	v_pk_mul_f32 v[28:29], v[28:29], v[34:35] op_sel_hi:[1,0]
	v_pk_mul_f32 v[22:23], v[22:23], v[34:35] op_sel_hi:[1,0]
	v_pk_mul_f32 v[30:31], v[30:31], v[34:35] op_sel_hi:[1,0]
	v_pk_mul_f32 v[16:17], v[16:17], v[34:35] op_sel_hi:[1,0]
	v_pk_mul_f32 v[24:25], v[24:25], v[34:35] op_sel_hi:[1,0]
	v_mul_f32_e32 v19, v18, v19
	v_mul_f32_e32 v18, 0xbfb8aa3b, v18
	v_mul_f32_e32 v33, v32, v33
	v_mul_f32_e32 v32, 0xbfb8aa3b, v32
	v_mul_f32_e32 v21, v20, v21
	v_mul_f32_e32 v20, 0xbfb8aa3b, v20
	v_mul_f32_e32 v29, v28, v29
	v_mul_f32_e32 v28, 0xbfb8aa3b, v28
	v_mul_f32_e32 v23, v22, v23
	v_mul_f32_e32 v22, 0xbfb8aa3b, v22
	v_mul_f32_e32 v31, v30, v31
	v_mul_f32_e32 v30, 0xbfb8aa3b, v30
	v_mul_f32_e32 v17, v16, v17
	v_mul_f32_e32 v16, 0xbfb8aa3b, v16
	v_mul_f32_e32 v25, v24, v25
	v_mul_f32_e32 v24, 0xbfb8aa3b, v24
	v_exp_f32_e32 v18, v18
	v_exp_f32_e32 v32, v32
	v_exp_f32_e32 v20, v20
	v_exp_f32_e32 v28, v28
	v_exp_f32_e32 v22, v22
	v_exp_f32_e32 v30, v30
	v_exp_f32_e32 v16, v16
	v_exp_f32_e32 v24, v24
	v_add_f32_e32 v18, 1.0, v18
	v_add_f32_e32 v32, 1.0, v32
	v_add_f32_e32 v20, 1.0, v20
	v_add_f32_e32 v28, 1.0, v28
	v_add_f32_e32 v22, 1.0, v22
	v_add_f32_e32 v30, 1.0, v30
	v_add_f32_e32 v16, 1.0, v16
	v_add_f32_e32 v24, 1.0, v24
	v_rcp_f32_e32 v18, v18
	v_rcp_f32_e32 v32, v32
	v_rcp_f32_e32 v20, v20
	v_rcp_f32_e32 v28, v28
	v_rcp_f32_e32 v22, v22
	v_rcp_f32_e32 v30, v30
	v_rcp_f32_e32 v16, v16
	v_rcp_f32_e32 v24, v24
	v_mul_f32_e32 v19, v19, v18
	v_mul_f32_e32 v32, v33, v32
	v_mul_f32_e32 v20, v21, v20
	v_mul_f32_e32 v21, v29, v28
	v_mul_f32_e32 v22, v23, v22
	v_mul_f32_e32 v23, v31, v30
	v_mul_f32_e32 v28, v17, v16
	v_mul_f32_e32 v24, v25, v24
	v_cvt_pk_bf16_f32 v16, v32, v20
	v_cvt_pk_bf16_f32 v17, v21, v22
	v_cvt_pk_bf16_f32 v18, v23, v28
	v_cvt_pk_bf16_f32 v19, v24, v19
	global_store_dwordx4 v[26:27], v[16:19], off
	s_nop 0
	s_andn2_b64 vcc, exec, s[4:5]
	v_mov_b32_e32 v17, v4
	v_mov_b32_e32 v4, v13
	v_mov_b32_e32 v13, v6
	v_mov_b32_e32 v6, v15
	v_mov_b32_e32 v15, v0
	v_mov_b32_e32 v0, v9
	v_mov_b32_e32 v9, v2
	v_mov_b32_e32 v2, v11
	v_mov_b32_e32 v16, v12
	v_mov_b32_e32 v12, v14
	v_mov_b32_e32 v14, v8
	v_mov_b32_e32 v8, v10
	v_add_u32_e32 v10, 0xb0, v144
	s_nop 0
	v_fmamk_f32 v11, v239, 0x3a800000, v154
	v_mul_f32_e32 v18, 0x4b800000, v11
	v_cmp_gt_f32_e64 s[0:1], s54, v11
	s_nop 1
	v_cndmask_b32_e64 v11, v11, v18, s[0:1]
	v_rsq_f32_e32 v18, v11
	v_mad_i64_i32 v[10:11], s[22:23], v10, s55, v[120:121]
	v_lshl_add_u64 v[10:11], v[10:11], 0, v[122:123]
	v_mul_f32_e32 v19, 0x45800000, v18
	v_cndmask_b32_e64 v18, v18, v19, s[0:1]
	v_pk_mul_f32 v[2:3], v[2:3], v[18:19] op_sel_hi:[1,0]
	v_pk_mul_f32 v[16:17], v[16:17], v[18:19] op_sel_hi:[1,0]
	v_pk_mul_f32 v[4:5], v[4:5], v[18:19] op_sel_hi:[1,0]
	v_pk_mul_f32 v[12:13], v[12:13], v[18:19] op_sel_hi:[1,0]
	v_pk_mul_f32 v[6:7], v[6:7], v[18:19] op_sel_hi:[1,0]
	v_pk_mul_f32 v[14:15], v[14:15], v[18:19] op_sel_hi:[1,0]
	v_pk_mul_f32 v[0:1], v[0:1], v[18:19] op_sel_hi:[1,0]
	v_pk_mul_f32 v[8:9], v[8:9], v[18:19] op_sel_hi:[1,0]
	v_mul_f32_e32 v3, v2, v3
	v_mul_f32_e32 v2, 0xbfb8aa3b, v2
	v_mul_f32_e32 v17, v16, v17
	v_mul_f32_e32 v16, 0xbfb8aa3b, v16
	v_mul_f32_e32 v5, v4, v5
	v_mul_f32_e32 v4, 0xbfb8aa3b, v4
	v_mul_f32_e32 v13, v12, v13
	v_mul_f32_e32 v12, 0xbfb8aa3b, v12
	v_mul_f32_e32 v7, v6, v7
	v_mul_f32_e32 v6, 0xbfb8aa3b, v6
	v_mul_f32_e32 v15, v14, v15
	v_mul_f32_e32 v14, 0xbfb8aa3b, v14
	v_mul_f32_e32 v1, v0, v1
	v_mul_f32_e32 v0, 0xbfb8aa3b, v0
	v_mul_f32_e32 v9, v8, v9
	v_mul_f32_e32 v8, 0xbfb8aa3b, v8
	v_exp_f32_e32 v2, v2
	v_exp_f32_e32 v16, v16
	v_exp_f32_e32 v4, v4
	v_exp_f32_e32 v12, v12
	v_exp_f32_e32 v6, v6
	v_exp_f32_e32 v14, v14
	v_exp_f32_e32 v0, v0
	v_exp_f32_e32 v8, v8
	v_add_f32_e32 v2, 1.0, v2
	v_add_f32_e32 v16, 1.0, v16
	v_add_f32_e32 v4, 1.0, v4
	v_add_f32_e32 v12, 1.0, v12
	v_add_f32_e32 v6, 1.0, v6
	v_add_f32_e32 v14, 1.0, v14
	v_add_f32_e32 v0, 1.0, v0
	v_add_f32_e32 v8, 1.0, v8
	v_rcp_f32_e32 v2, v2
	v_rcp_f32_e32 v16, v16
	v_rcp_f32_e32 v4, v4
	v_rcp_f32_e32 v12, v12
	v_rcp_f32_e32 v6, v6
	v_rcp_f32_e32 v14, v14
	v_rcp_f32_e32 v0, v0
	v_rcp_f32_e32 v8, v8
	v_mul_f32_e32 v3, v3, v2
	s_mov_b64 s[0:1], -1
	v_mul_f32_e32 v16, v17, v16
	v_mul_f32_e32 v4, v5, v4
	v_mul_f32_e32 v5, v13, v12
	v_mul_f32_e32 v6, v7, v6
	v_mul_f32_e32 v7, v15, v14
	v_mul_f32_e32 v12, v1, v0
	v_mul_f32_e32 v8, v9, v8
	v_cvt_pk_bf16_f32 v0, v16, v4
	v_cvt_pk_bf16_f32 v1, v5, v6
	v_cvt_pk_bf16_f32 v2, v7, v12
	v_cvt_pk_bf16_f32 v3, v8, v3
	global_store_dwordx4 v[10:11], v[0:3], off
	s_cbranch_vccnz .LBB0_1554
	s_andn2_b64 vcc, exec, s[6:7]
	s_cbranch_vccnz .LBB0_1553
	s_barrier
	s_branch .LBB0_1553
